# cvhost: hosted stores and next loads both issued just before the step-A wait (step-A wait vmcnt(5/3/2), step-B strict)
# baseline (speedup 1.0000x reference)
; template <int NB>
; __device__ __forceinline__ void p0_batch(int it0, int stride, int lane, const P0Ptrs& a) {
;     ...
;     for (int q = 0; q < NB; ++q) {
;         const float gs = d[q].gs; const bool hk = d[q].ks != nullptr;
;         const f32x4 t0 = hk ? s0[q] * gs : (f32x4){gs, gs, gs, gs}, t1 = hk ? s1[q] * gs : (f32x4){gs, gs, gs, gs};
; #pragma unroll
;         for (int i = 0; i < 4; ++i) { v[q][i] *= t0[i]; v[q][4 + i] *= t1[i]; }
.LBB0_759:
	s_add_i32 s98, s87, -1
	s_cmp_gt_u32 s98, 19
	s_cbranch_scc1 .Lcv_predone
	s_cmp_gt_u32 s32, 6
	s_cbranch_scc1 .Lcv_nomul
	v_mul_f32_e32 v238, v237, v238
	v_mul_f32_e32 v239, v237, v239
	v_mul_f32_e32 v240, v237, v240
	v_mul_f32_e32 v241, v237, v241
	v_mul_f32_e32 v242, v237, v242
	v_mul_f32_e32 v243, v237, v243
	v_mul_f32_e32 v244, v237, v244
	v_mul_f32_e32 v245, v237, v245

; __device__ __forceinline__ P0Desc p0_desc(int r, int lane, const P0Ptrs& a) {
;     const int kk = lane >> 3, n4 = (lane & 7) * 4; P0Desc d; d.gs = 1.f;
;     int kb, n, sc, nsrc, ldt; const float* W; bf16_t* WT; const float* ks;
;     if (r < F_O) { kb = r >> 6; n = 32 * (r & 63) + n4; sc = n; W = a.w_o; nsrc = 2048; WT = a.WoT; ldt = 2048; ks = (kb < 16) ? a.on_a : (a.on_c - 1024); }
;     else if ((r -= F_O) < F_UP) { kb = r / 352; n = 32 * (r % 352) + n4; sc = ((n >> 7) & 1) * DFF + (n >> 8) * 128 + (n & 127); W = a.w_up; nsrc = 2 * DFF; WT = a.WupT; ldt = 2048; ks = a.ffn_g; }
;     else if ((r -= F_UP) < F_DN) { kb = r >> 6; n = 32 * (r & 63) + n4; sc = n; W = a.w_dn; nsrc = 2048; WT = a.WdT; ldt = DFF; ks = nullptr; }
;     else if ((r -= F_DN) < F_IN) { kb = r >> 7; n = 32 * (r & 127) + n4;
;         if (n < 1024) sc = n; else if (n < 2048) sc = n + 64; else sc = (((n >> 7) & 1) ? 3136 : 2112) + 128 * ((n - 2048) >> 8) + (n & 127);
;         W = a.w_in; nsrc = INW; WT = a.WinT; ldt = 2048; ks = a.attn_g; }
;     else if ((r -= F_IN) < F_Q) { kb = r >> 5; n = 32 * (6 * ((r & 31) >> 2) + (r & 3)) + n4; sc = n; W = a.w_qb; nsrc = 1536; WT = a.WqT; ldt = 2048; ks = a.qa_g; d.gs = QSCALE; }
;     else { r -= F_Q; kb = r >> 6; n = 32 * (r & 63) + n4; sc = n; W = a.w_kvb; nsrc = 2048; WT = a.WkvT; ldt = 2048; ks = a.kva_g; }
;     const int k0 = 64 * kb + 8 * kk;
;     d.src = W + (size_t)k0 * nsrc + sc; d.nsrc = nsrc; d.dst = WT + (size_t)n * ldt + k0; d.ldt = ldt; d.ks = ks ? ks + k0 : nullptr;
;     return d;
; }
.Lcv_predone:
	s_cmp_gt_u32 s87, 21
	s_cbranch_scc1 .Lcv_done
	s_cmp_gt_u32 s87, 19
	s_cbranch_scc1 .Lcv_inc
	s_and_b32 s98, s87, 3
	s_cmp_lg_u32 s98, 0
	s_cbranch_scc1 .Lcv_loads
	s_add_i32 s32, s32, 1
	v_readfirstlane_b32 s99, v0
	s_waitcnt lgkmcnt(0)
	s_and_b32 s98, s2, 0xff
	s_lshr_b32 s90, s98, 3
	s_and_b32 s98, s98, 7
	s_lshl_b32 s98, s98, 3
	s_lshr_b32 s99, s99, 6
	s_add_i32 s91, s98, s99
	s_cmp_eq_u32 s32, 0
	s_cbranch_scc1 .Lcv_t0
	s_cmp_lt_u32 s32, 7
	s_cbranch_scc1 .Lcv_t1
	s_add_i32 s98, s32, -7
	s_lshl_b32 s98, s98, 5
	s_add_i32 s90, s90, s98
	s_cmp_ge_u32 s90, 0x58
	s_cselect_b32 s98, 32, 0
	s_sub_i32 s90, s90, s98
	s_lshl_b32 s98, s90, 19
	s_lshl_b32 s99, s91, 7
	s_add_i32 s98, s98, s99
	s_add_u32 s88, s88, s98
	s_addc_u32 s89, s89, 0
	s_mul_i32 s98, s91, 0x58000
	s_lshl_b32 s99, s90, 7
	s_add_i32 s98, s98, s99
	s_add_i32 s98, s98, 0x6900000
	s_add_u32 s92, s28, s98
	s_addc_u32 s93, s29, 0
	s_mov_b32 s90, 0x2000
	s_mov_b32 s91, 0x2c00
	s_branch .Lcv_s2done

.Lcv_done:
	v_lshl_add_u64 v[112:113], s[28:29], 0, v[146:147]
	s_mov_b64 s[54:55], 0x18fc0000
	s_mov_b32 m0, s78
	v_lshl_add_u64 v[100:101], v[112:113], 0, s[54:55]
	s_add_i32 s98, s87, -2
	s_cmp_lt_u32 s98, 19
	s_cbranch_scc1 .Lcv_wa5
	s_cmp_eq_u32 s87, 1
	s_cbranch_scc1 .Lcv_wa3
	s_cmp_eq_u32 s87, 21
	s_cbranch_scc1 .Lcv_wa2
	s_waitcnt vmcnt(0)
	s_branch .Lcv_wad

.Lcv_wad:
	s_barrier
	global_load_lds_dwordx4 v[100:101], off
	v_lshl_add_u64 v[100:101], v[112:113], 0, s[38:39]
	s_add_i32 m0, s78, 0x2000
	v_lshl_add_u64 v[136:137], s[28:29], 0, v[144:145]
	global_load_lds_dwordx4 v[100:101], off
	v_lshl_add_u64 v[100:101], v[136:137], 0, s[40:41]
	s_add_i32 m0, s78, 0x4000
	v_lshl_add_u64 v[134:135], s[28:29], 0, v[148:149]
	global_load_lds_dwordx4 v[100:101], off
	v_lshl_add_u64 v[100:101], v[134:135], 0, s[42:43]
	s_mov_b32 m0, s58
	global_load_lds_dwordx4 v[100:101], off
	v_lshl_add_u64 v[100:101], v[134:135], 0, s[44:45]
	s_mov_b32 m0, s77
	global_load_lds_dwordx4 v[100:101], off
	v_exp_f32_e32 v1, v249
	v_exp_f32_e32 v101, v84
	v_exp_f32_e32 v103, v85
	v_exp_f32_e32 v205, v89
	v_exp_f32_e32 v206, v90
	v_sub_f32_e32 v102, v70, v140
	v_sub_f32_e32 v204, v74, v140
	v_exp_f32_e32 v160, v88
	v_sub_f32_e32 v88, v69, v140
	v_sub_f32_e32 v158, v72, v140
	v_exp_f32_e32 v154, v86
	v_exp_f32_e32 v159, v87
	v_exp_f32_e32 v208, v91
	v_exp_f32_e32 v209, v92
	v_exp_f32_e32 v210, v93
	v_exp_f32_e32 v211, v94
	v_sub_f32_e32 v155, v71, v140
	v_sub_f32_e32 v161, v73, v140
	v_sub_f32_e32 v207, v75, v140
	ds_read_b128 v[68:71], v178 offset:32768
	ds_read_b128 v[84:87], v178 offset:36864
	s_waitcnt lgkmcnt(0)
	ds_read_b128 v[104:107], v179 offset:32768
	ds_read_b128 v[108:111], v179 offset:36864
	v_mfma_f32_32x32x16_bf16 v[68:83], v[68:71], v[126:129], 0
	v_cvt_pk_bf16_f32 v100, v1, v101
	v_exp_f32_e32 v226, v99
	v_add_f32_e32 v227, 0, v1
	v_exp_f32_e32 v1, v88
	v_mfma_f32_32x32x16_bf16 v[84:99], v[84:87], v[126:129], 0
	v_add_f32_e32 v228, 0, v101
	v_cvt_pk_bf16_f32 v101, v103, v154
	s_waitcnt lgkmcnt(0)
	ds_read_b128 v[130:133], v177 offset:32768
	ds_read_b128 v[150:153], v177 offset:36864
	v_mfma_f32_32x32x16_bf16 v[68:83], v[104:107], v[122:125], v[68:83]
	v_exp_f32_e32 v229, v102
	v_cvt_pk_bf16_f32 v102, v159, v160
	v_add_f32_e32 v230, 0, v103
	v_mfma_f32_32x32x16_bf16 v[84:99], v[108:111], v[122:125], v[84:99]
	v_add_f32_e32 v105, 0, v154
	v_cvt_pk_bf16_f32 v103, v205, v206
	v_exp_f32_e32 v231, v155
	s_waitcnt lgkmcnt(0)
	ds_read_b128 v[106:109], v176 offset:32768
	ds_read_b128 v[154:157], v176 offset:36864
	v_mfma_f32_32x32x16_bf16 v[68:83], v[130:133], v[118:121], v[68:83]
	v_permlane32_swap_b32_e32 v100, v102
	v_exp_f32_e32 v232, v158
	v_add_f32_e32 v227, v159, v227
	v_mfma_f32_32x32x16_bf16 v[84:99], v[150:153], v[118:121], v[84:99]
	v_permlane32_swap_b32_e32 v101, v103
	v_exp_f32_e32 v233, v161
	v_add_f32_e32 v228, v160, v228
	s_waitcnt lgkmcnt(0)
	ds_read_b128 v[130:133], v178 offset:40960
	ds_read_b128 v[150:153], v178 offset:45056
	ds_read_b128 v[158:161], v171
	v_mfma_f32_32x32x16_bf16 v[68:83], v[106:109], v[114:117], v[68:83]
	v_cvt_pk_bf16_f32 v104, v208, v209
	v_exp_f32_e32 v234, v204
	v_add_f32_e32 v230, v205, v230
	v_mfma_f32_32x32x16_bf16 v[84:99], v[154:157], v[114:117], v[84:99]
	v_add_f32_e32 v236, v206, v105
	v_cvt_pk_bf16_f32 v105, v210, v211
	v_exp_f32_e32 v235, v207
	s_waitcnt lgkmcnt(0)
	ds_read_b128 v[108:111], v179 offset:40960
	ds_read_b128 v[154:157], v179 offset:45056
	ds_read_b128 v[204:207], v170
	v_mfma_f32_32x32x16_bf16 v[68:83], v[130:133], v[158:161], v[68:83]
	v_cvt_pk_bf16_f32 v106, v212, v213
	v_exp_f32_e32 v216, v216
	v_add_f32_e32 v227, v208, v227
	v_mfma_f32_32x32x16_bf16 v[84:99], v[150:153], v[158:161], v[84:99]
	v_cvt_pk_bf16_f32 v107, v214, v215
	v_exp_f32_e32 v217, v217
	v_add_f32_e32 v228, v209, v228
	s_waitcnt lgkmcnt(0)
	ds_read_b128 v[130:133], v177 offset:40960
	ds_read_b128 v[150:153], v177 offset:45056
	ds_read_b128 v[158:161], v169
	v_mfma_f32_32x32x16_bf16 v[68:83], v[108:111], v[204:207], v[68:83]
	v_permlane32_swap_b32_e32 v104, v106
	v_exp_f32_e32 v218, v218
	v_add_f32_e32 v230, v210, v230
	v_mfma_f32_32x32x16_bf16 v[84:99], v[154:157], v[204:207], v[84:99]
	v_add_f32_e32 v111, v211, v236
	v_permlane32_swap_b32_e32 v105, v107
	v_exp_f32_e32 v219, v219
	s_waitcnt lgkmcnt(0)
	ds_read_b128 v[154:157], v176 offset:40960
	ds_read_b128 v[204:207], v176 offset:45056
	ds_read_b128 v[208:211], v168
	v_mfma_f32_32x32x16_bf16 v[68:83], v[130:133], v[158:161], v[68:83]
	v_cvt_pk_bf16_f32 v108, v226, v1
	v_exp_f32_e32 v220, v220
	v_add_f32_e32 v212, v212, v227
	v_mfma_f32_32x32x16_bf16 v[84:99], v[150:153], v[158:161], v[84:99]
	v_cvt_pk_bf16_f32 v109, v229, v231
	v_exp_f32_e32 v221, v221
	v_add_f32_e32 v213, v213, v228
	s_waitcnt lgkmcnt(0)
	ds_read_b128 v[130:133], v178 offset:49152
	ds_read_b128 v[150:153], v178 offset:53248
	ds_read_b128 v[158:161], v171 offset:4096
	v_mfma_f32_32x32x16_bf16 v[68:83], v[154:157], v[208:211], v[68:83]
	v_cvt_pk_bf16_f32 v110, v232, v233
	v_exp_f32_e32 v222, v222
	v_add_f32_e32 v214, v214, v230
	v_mfma_f32_32x32x16_bf16 v[84:99], v[204:207], v[208:211], v[84:99]
	v_add_f32_e32 v215, v215, v111
	v_cvt_pk_bf16_f32 v111, v234, v235
	v_exp_f32_e32 v223, v223
	s_waitcnt lgkmcnt(0)
	ds_read_b128 v[154:157], v179 offset:49152
	ds_read_b128 v[204:207], v179 offset:53248
	ds_read_b128 v[208:211], v170 offset:4096
	v_mfma_f32_32x32x16_bf16 v[68:83], v[130:133], v[158:161], v[68:83]
	v_add_f32_e32 v1, v1, v213
	v_permlane32_swap_b32_e32 v108, v110
	v_add_f32_e32 v226, v226, v212
	v_mfma_f32_32x32x16_bf16 v[84:99], v[150:153], v[158:161], v[84:99]
	v_add_f32_e32 v131, v229, v214
	v_add_f32_e32 v132, v231, v215
	v_permlane32_swap_b32_e32 v109, v111
	s_waitcnt lgkmcnt(0)
	ds_read_b128 v[150:153], v177 offset:49152
	ds_read_b128 v[158:161], v177 offset:53248
	ds_read_b128 v[212:215], v169 offset:4096
	v_mfma_f32_32x32x16_bf16 v[68:83], v[154:157], v[208:211], v[68:83]
	v_add_f32_e32 v133, v232, v226
	v_add_f32_e32 v1, v233, v1
	v_cvt_pk_bf16_f32 v130, v216, v217
	v_mfma_f32_32x32x16_bf16 v[84:99], v[204:207], v[208:211], v[84:99]
	v_add_f32_e32 v226, v234, v131
	v_cvt_pk_bf16_f32 v131, v218, v219
	v_add_f32_e32 v227, v235, v132
	s_waitcnt lgkmcnt(0)
	ds_read_b128 v[154:157], v176 offset:49152
	ds_read_b128 v[204:207], v176 offset:53248
	ds_read_b128 v[208:211], v168 offset:4096
	v_mfma_f32_32x32x16_bf16 v[68:83], v[150:153], v[212:215], v[68:83]
	v_add_f32_e32 v1, v217, v1
	v_cvt_pk_bf16_f32 v132, v220, v221
	v_add_f32_e32 v216, v216, v133
	v_mfma_f32_32x32x16_bf16 v[84:99], v[158:161], v[212:215], v[84:99]
	v_cvt_pk_bf16_f32 v133, v222, v223
	v_add_f32_e32 v150, v218, v226
	v_add_f32_e32 v151, v219, v227
	s_waitcnt lgkmcnt(0)
	v_mfma_f32_32x32x16_bf16 v[68:83], v[154:157], v[208:211], v[68:83]
	v_add_f32_e32 v1, v221, v1
	v_permlane32_swap_b32_e32 v130, v132
	v_add_f32_e32 v152, v220, v216
	v_mfma_f32_32x32x16_bf16 v[84:99], v[204:207], v[208:211], v[84:99]
	v_permlane32_swap_b32_e32 v131, v133
	v_add_f32_e32 v150, v222, v150
	v_add_f32_e32 v151, v223, v151
	v_add_f32_e32 v1, v152, v1
	v_add_f32_e32 v150, v150, v151
	v_add_f32_e32 v205, v1, v150
	v_mov_b32_e32 v206, v205
	s_nop 1
	v_permlane32_swap_b32_e32 v205, v206
